# K fragment prefetch distance 2 pairs instead of 3 (fewer LDS reads in flight)
# speedup vs baseline: 1.0139x; 1.0011x over previous
; __device__ __forceinline__ int lane_id_v() { int l; asm volatile("v_mbcnt_lo_u32_b32 %0, -1, 0\n\tv_mbcnt_hi_u32_b32 %0, -1, %0" : "=v"(l)); return l; }
; __device__ __forceinline__ int v_rd_base(int lane) { return ((lane & 3) << 3) | (((lane >> 2) & 3) << 6) | (((lane >> 4) & 1) << 5) | (((lane >> 5) & 1) << 8); }
; #define WAITV() asm volatile("s_waitcnt vmcnt(0)" ::: "memory")
; template <int DN, int DV, bool MASK> ...
;     ...
;   const int wid = wave_, lane = lane_id_v(), r32 = lane & 31, hi = lane >> 5;
;   char* Vl = lds; char* Knl = lds + VB; char* Krl = lds + VB + KNB;
;   float* wsf = (float*)(lds + 3 * BUF) + wid * 64; float* li_l = wsf; float* al_l = wsf + 32;
;   float m_reg = -1e30f, l_reg = 0; f32x16 o[NCB] = {}; bf16x8 qr[NQR];
;   const bf16_t* Qw = Qb + (MASK ? (long)r32 * ldq + wid * 64 : (long)(wid * 32 + r32) * ldq) + hi * 8;
; #pragma unroll
;   for (int d0 = 0; d0 < NQR; ++d0) qr[d0] = *reinterpret_cast<const bf16x8*>(Qw + d0 * 16);
;   char* qrl = lds + 3 * BUF + 2048 + wid * 4096 + lane * 16;
;   if constexpr (DN > 0) {
; #pragma unroll
;     for (int d0 = 0; d0 < 4; ++d0) *reinterpret_cast<bf16x8*>(qrl + d0 * 1024) = *reinterpret_cast<const bf16x8*>(Qw + DN + d0 * 16);
;   }
;   int offV[NVC], offK[NKC > 0 ? NKC : 1], offR;
; #pragma unroll
;   for (int i = 0; i < NVC; ++i) { const int ch = wid * NVC + i, sub = ch * 2 + (lane >> 5), kk = (sub / NCB) * 8 + ((lane & 31) >> 2), col = (sub % NCB) * 32 + (lane & 3) * 8;
;     const int k = (kk & ~0xC) | ((kk & 4) << 1) | ((kk & 8) >> 1); offV[i] = k * ldv + col; }
; #pragma unroll
;   for (int i = 0; i < NKC; ++i) { const int ch = wid * NKC + i, row = ch * 4 + (lane >> 4), cb = ((lane & 15) * 16) ^ ((row & 15) << 4); offK[i] = row * ldkn + (cb >> 1); }
;   { const int row = wid * 8 + (lane >> 3), cb = ((lane & 7) * 16) ^ (((row >> 1) & 7) << 4); offR = row * ldkr + (cb >> 1); }
;   const int vb0 = (int)(uintptr_t)Vl + v_rd_base(lane);
;   const int qd = qpos0 + (MASK ? 0 : wid * 32) + r32 - 4 * hi;
;     ...
;   const int q0w = qpos0 + (MASK ? 0 : wid * 32);
;     ...
;   f32x16 pA0, pA1, pB0, pB1; float alA, alB; bf16x8 pa0, pa1, pa2, pa3;
;   int bp = 0, bc = BUF, bn = 2 * BUF;
;   DMA(0, 0); DMA(1, BUF); WAITV(); __syncthreads();
.LBB0_818:
	s_and_b32 s97, s2, 15
	s_ashr_i32 s69, s68, 31
	s_mul_i32 s1, s68, 0x1800
	s_mul_hi_i32 s0, s68, 0x1800
	s_add_u32 s1, s34, s1
	s_addc_u32 s2, s35, s0
	s_mul_i32 s0, s97, 0x180
	s_add_u32 s0, s1, s0
	s_addc_u32 s1, s2, 0
	v_mbcnt_lo_u32_b32 v249, -1, 0
	v_mbcnt_hi_u32_b32 v249, -1, v249
	s_waitcnt lgkmcnt(0)
	v_and_b32_e32 v173, 31, v249
	v_lshrrev_b32_e32 v174, 5, v249
	v_or_b32_e32 v175, s46, v173
	v_mov_b64_e32 v[64:65], s[0:1]
	s_movk_i32 s12, 0x1800
	v_mad_u64_u32 v[64:65], s[14:15], v175, s12, v[64:65]
	v_lshlrev_b32_e32 v66, 4, v174
	v_mov_b32_e32 v67, 0
	v_lshl_add_u64 v[64:65], v[64:65], 0, v[66:67]
	global_load_dwordx4 v[96:99], v[64:65], off offset:0
	global_load_dwordx4 v[100:103], v[64:65], off offset:32
	global_load_dwordx4 v[104:107], v[64:65], off offset:64
	global_load_dwordx4 v[108:111], v[64:65], off offset:96
	global_load_dwordx4 v[112:115], v[64:65], off offset:128
	global_load_dwordx4 v[116:119], v[64:65], off offset:160
	global_load_dwordx4 v[120:123], v[64:65], off offset:192
	global_load_dwordx4 v[124:127], v[64:65], off offset:224
	global_load_dwordx4 v[176:179], v[64:65], off offset:256
	global_load_dwordx4 v[180:183], v[64:65], off offset:288
	global_load_dwordx4 v[184:187], v[64:65], off offset:320
	global_load_dwordx4 v[188:191], v[64:65], off offset:352
	v_and_b32_e32 v66, 15, v173
	v_xor_b32_e32 v66, v66, v174
	v_lshlrev_b32_e32 v66, 4, v66
	v_lshl_or_b32 v152, v173, 8, v66
	v_xor_b32_e32 v153, 32, v152
	v_xor_b32_e32 v154, 64, v152
	v_xor_b32_e32 v155, 96, v152
	v_xor_b32_e32 v156, 128, v152
	v_xor_b32_e32 v157, 160, v152
	v_xor_b32_e32 v158, 192, v152
	v_xor_b32_e32 v159, 224, v152
	v_bfe_u32 v66, v173, 1, 3
	v_xor_b32_e32 v66, v66, v174
	v_lshlrev_b32_e32 v66, 4, v66
	v_lshl_or_b32 v160, v173, 7, v66
	v_xor_b32_e32 v161, 32, v160
	v_xor_b32_e32 v162, 64, v160
	v_xor_b32_e32 v163, 96, v160
	v_lshlrev_b32_e32 v66, 3, v249
	v_and_b32_e32 v67, 24, v66
	v_and_b32_e32 v68, 0x100, v66
	v_or_b32_e32 v67, v67, v68
	v_lshlrev_b32_e32 v68, 4, v249
	v_and_b32_e32 v68, 0xc0, v68
	v_or_b32_e32 v67, v67, v68
	v_lshlrev_b32_e32 v68, 1, v249
	v_and_b32_e32 v68, 32, v68
	v_or_b32_e32 v67, v67, v68
	v_add_u32_e32 v164, 0xc000, v67
	v_lshl_add_u32 v248, v249, 4, s75
	v_lshrrev_b32_e32 v66, 2, v173
	v_add_u32_e32 v66, s77, v66
	v_and_b32_e32 v67, 4, v66
	v_and_b32_e32 v68, 8, v66
	v_and_b32_e32 v66, 0xfffffff3, v66
	v_lshl_or_b32 v66, v67, 1, v66
	v_lshrrev_b32_e32 v68, 1, v68
	v_or_b32_e32 v66, v66, v68
	v_and_b32_e32 v67, 3, v249
	v_lshlrev_b32_e32 v67, 4, v67
	v_lshl_or_b32 v67, v174, 6, v67
	v_lshl_add_u32 v66, v66, 13, v67
	v_add_u32_e32 v165, 0x100, v66
	v_add_u32_e32 v169, 0x180, v66
	v_lshrrev_b32_e32 v66, 4, v249
	v_add_u32_e32 v66, s77, v66
	v_and_b32_e32 v67, 15, v249
	v_xor_b32_e32 v68, v67, v66
	v_and_b32_e32 v68, 15, v68
	v_lshlrev_b32_e32 v68, 4, v68
	v_lshl_add_u32 v166, v66, 13, v68
	v_add_u32_e32 v66, 4, v66
	v_xor_b32_e32 v68, v67, v66
	v_and_b32_e32 v68, 15, v68
	v_lshlrev_b32_e32 v68, 4, v68
	v_lshl_add_u32 v167, v66, 13, v68
	v_lshrrev_b32_e32 v66, 3, v249
	v_add_u32_e32 v66, s77, v66
	v_bfe_u32 v67, v66, 1, 3
	v_and_b32_e32 v68, 7, v249
	v_xor_b32_e32 v67, v67, v68
	v_lshlrev_b32_e32 v67, 4, v67
	v_lshl_add_u32 v168, v66, 7, v67
	s_lshl_b32 s0, s97, 9
	s_add_u32 s79, s38, s0
	s_addc_u32 s26, s39, 0
	s_ashr_i32 s71, s70, 31
	s_lshl_b64 s[0:1], s[70:71], 13
	s_add_u32 s4, s79, s0
	s_addc_u32 s5, s26, s1
	s_add_u32 s6, s4, 0x80000
	s_addc_u32 s7, s5, 0
	s_lshl_b64 s[0:1], s[70:71], 7
	s_add_u32 s8, s18, s0
	s_addc_u32 s9, s19, s1
	s_add_i32 m0, s82, 0
	s_nop 0
	global_load_lds_dwordx4 v166, s[4:5]
	s_add_i32 m0, s82, 1024
	s_nop 0
	global_load_lds_dwordx4 v167, s[4:5]
	s_add_i32 m0, s83, 16384
	s_nop 0
	global_load_lds_dwordx4 v168, s[8:9]
	s_add_u32 s8, s8, 0x2000
	s_addc_u32 s9, s9, 0
	s_mov_b32 s10, 0
	v_mov_b32_e32 v0, 0
	v_mov_b32_e32 v1, 0
	v_mov_b32_e32 v2, 0
	v_mov_b32_e32 v3, 0
	v_mov_b32_e32 v4, 0
	v_mov_b32_e32 v5, 0
	v_mov_b32_e32 v6, 0
	v_mov_b32_e32 v7, 0
	v_mov_b32_e32 v8, 0
	v_mov_b32_e32 v9, 0
	v_mov_b32_e32 v10, 0
	v_mov_b32_e32 v11, 0
	v_mov_b32_e32 v12, 0
	v_mov_b32_e32 v13, 0
	v_mov_b32_e32 v14, 0
	v_mov_b32_e32 v15, 0
	v_mov_b32_e32 v48, 0
	v_mov_b32_e32 v49, 0
	v_mov_b32_e32 v50, 0
	v_mov_b32_e32 v51, 0
	v_mov_b32_e32 v52, 0
	v_mov_b32_e32 v53, 0
	v_mov_b32_e32 v54, 0
	v_mov_b32_e32 v55, 0
	v_mov_b32_e32 v56, 0
	v_mov_b32_e32 v57, 0
	v_mov_b32_e32 v58, 0
	v_mov_b32_e32 v59, 0
	v_mov_b32_e32 v60, 0
	v_mov_b32_e32 v61, 0
	v_mov_b32_e32 v62, 0
	v_mov_b32_e32 v63, 0
	v_mov_b32_e32 v32, 0
	v_mov_b32_e32 v33, 0
	v_mov_b32_e32 v34, 0
	v_mov_b32_e32 v35, 0
	v_mov_b32_e32 v36, 0
	v_mov_b32_e32 v37, 0
	v_mov_b32_e32 v38, 0
	v_mov_b32_e32 v39, 0
	v_mov_b32_e32 v40, 0
	v_mov_b32_e32 v41, 0
	v_mov_b32_e32 v42, 0
	v_mov_b32_e32 v43, 0
	v_mov_b32_e32 v44, 0
	v_mov_b32_e32 v45, 0
	v_mov_b32_e32 v46, 0
	v_mov_b32_e32 v47, 0
	v_mov_b32_e32 v16, 0
	v_mov_b32_e32 v17, 0
	v_mov_b32_e32 v18, 0
	v_mov_b32_e32 v19, 0
	v_mov_b32_e32 v20, 0
	v_mov_b32_e32 v21, 0
	v_mov_b32_e32 v22, 0
	v_mov_b32_e32 v23, 0
	v_mov_b32_e32 v24, 0
	v_mov_b32_e32 v25, 0
	v_mov_b32_e32 v26, 0
	v_mov_b32_e32 v27, 0
	v_mov_b32_e32 v28, 0
	v_mov_b32_e32 v29, 0
	v_mov_b32_e32 v30, 0
	v_mov_b32_e32 v31, 0
	v_mov_b32_e32 v170, 0
	s_waitcnt vmcnt(0)
	ds_write_b128 v248, v[176:179] offset:0
	ds_write_b128 v248, v[180:183] offset:1024
	ds_write_b128 v248, v[184:187] offset:2048
	ds_write_b128 v248, v[188:191] offset:3072
	s_waitcnt lgkmcnt(0)
	s_barrier
; __device__ __forceinline__ void partialSM(f32x16& p0, f32x16& p1, float& m_reg, float& alpha, const float C, const float THRS) {
;   float pmax = p0[0];
; #pragma unroll
;   for (int r = 1; r < 16; ++r) pmax = fmaxf(pmax, p0[r]);
; #pragma unroll
;   for (int r = 0; r < 16; ++r) pmax = fmaxf(pmax, p1[r]);
;   { auto rr = __builtin_amdgcn_permlane32_swap(__float_as_uint(pmax), __float_as_uint(pmax), false, false);
;     pmax = fmaxf(__uint_as_float(rr[0]), __uint_as_float(rr[1])); }
;   float mn;
;   if (__builtin_expect(__all(pmax - m_reg <= THRS), 1)) { mn = m_reg; alpha = 1.f; }
;   else { mn = fmaxf(m_reg, pmax); alpha = __builtin_amdgcn_exp2f((m_reg - mn) * C); m_reg = mn; }
;   const float mnC = -mn * C;
; #pragma unroll
;   for (int r = 0; r < 16; ++r) p0[r] = fmaf(p0[r], C, mnC);
; #pragma unroll
;   for (int r = 0; r < 16; ++r) p1[r] = fmaf(p1[r], C, mnC);
; #pragma unroll
;   for (int r = 0; r < 16; ++r) p0[r] = __builtin_amdgcn_exp2f(p0[r]);
; }
; template <int DN>
; __device__ __forceinline__ void qkt(f32x16& p0, f32x16& p1, const char* Kn, const char* Kr, const bf16x8* qr, const char* qrl, int r32, int hi) {
;   p0 = f32x16{}; p1 = f32x16{};
;   if constexpr (DN > 0) {
; #pragma unroll
;     for (int d0 = 0; d0 < DN / 16; ++d0) { const int cb = (d0 * 16 + hi * 8) * 2;
;       bf16x8 b0 = *reinterpret_cast<const bf16x8*>(Kn + KSWZ(r32, cb));
;       bf16x8 b1 = *reinterpret_cast<const bf16x8*>(Kn + KSWZ(32 + r32, cb));
;       p0 = __builtin_amdgcn_mfma_f32_32x32x16_bf16(b0, qr[d0], p0, 0, 0, 0);
;       p1 = __builtin_amdgcn_mfma_f32_32x32x16_bf16(b1, qr[d0], p1, 0, 0, 0); }
;   }
; #pragma unroll
;   for (int d0 = 0; d0 < 4; ++d0) { const int cb = (d0 * 16 + hi * 8) * 2;
;     bf16x8 b0 = *reinterpret_cast<const bf16x8*>(Kr + KSWZ64(r32, cb));
;     bf16x8 b1 = *reinterpret_cast<const bf16x8*>(Kr + KSWZ64(32 + r32, cb));
;     bf16x8 q; if constexpr (DN > 0) q = *reinterpret_cast<const bf16x8*>(qrl + d0 * 1024); else q = qr[d0];
;     p0 = __builtin_amdgcn_mfma_f32_32x32x16_bf16(b0, q, p0, 0, 0, 0);
;     p1 = __builtin_amdgcn_mfma_f32_32x32x16_bf16(b1, q, p1, 0, 0, 0); }
; }
	ds_read_b128 v[224:227], v152 offset:0
	ds_read_b128 v[228:231], v152 offset:8192
	ds_read_b128 v[232:235], v153 offset:0
	ds_read_b128 v[236:239], v153 offset:8192
	s_add_i32 m0, s82, 49152
	s_nop 0
	global_load_lds_dwordx4 v165, s[4:5]
	s_add_i32 m0, s82, 50176
	s_nop 0
	global_load_lds_dwordx4 v169, s[4:5]
	s_add_i32 m0, s82, 24576
	s_nop 0
	global_load_lds_dwordx4 v166, s[6:7]
	s_add_i32 m0, s82, 25600
	s_nop 0
	global_load_lds_dwordx4 v167, s[6:7]
	s_add_i32 m0, s83, 40960
	s_nop 0
	global_load_lds_dwordx4 v168, s[8:9]
	s_mov_b64 s[4:5], s[6:7]
	s_add_u32 s6, s6, 0x80000
	s_addc_u32 s7, s7, 0
	s_add_u32 s8, s8, 0x2000
	s_addc_u32 s9, s9, 0
	s_waitcnt lgkmcnt(2)
	v_mfma_f32_32x32x16_bf16 v[64:79], v[224:227], v[96:99], 0
	v_mfma_f32_32x32x16_bf16 v[80:95], v[228:231], v[96:99], 0
	ds_read_b128 v[240:243], v154 offset:0
	ds_read_b128 v[244:247], v154 offset:8192
	s_waitcnt lgkmcnt(2)
	v_mfma_f32_32x32x16_bf16 v[64:79], v[232:235], v[100:103], v[64:79]
	v_mfma_f32_32x32x16_bf16 v[80:95], v[236:239], v[100:103], v[80:95]
	ds_read_b128 v[224:227], v155 offset:0
	ds_read_b128 v[228:231], v155 offset:8192
	s_waitcnt lgkmcnt(2)
	v_mfma_f32_32x32x16_bf16 v[64:79], v[240:243], v[104:107], v[64:79]
	v_mfma_f32_32x32x16_bf16 v[80:95], v[244:247], v[104:107], v[80:95]
	ds_read_b128 v[232:235], v156 offset:0
	ds_read_b128 v[236:239], v156 offset:8192
	s_waitcnt lgkmcnt(2)
	v_mfma_f32_32x32x16_bf16 v[64:79], v[224:227], v[108:111], v[64:79]
	v_mfma_f32_32x32x16_bf16 v[80:95], v[228:231], v[108:111], v[80:95]
	ds_read_b128 v[240:243], v157 offset:0
	ds_read_b128 v[244:247], v157 offset:8192
	s_waitcnt lgkmcnt(2)
	v_mfma_f32_32x32x16_bf16 v[64:79], v[232:235], v[112:115], v[64:79]
	v_mfma_f32_32x32x16_bf16 v[80:95], v[236:239], v[112:115], v[80:95]
	ds_read_b128 v[224:227], v158 offset:0
	ds_read_b128 v[228:231], v158 offset:8192
	s_waitcnt lgkmcnt(2)
	v_mfma_f32_32x32x16_bf16 v[64:79], v[240:243], v[116:119], v[64:79]
	v_mfma_f32_32x32x16_bf16 v[80:95], v[244:247], v[116:119], v[80:95]
	ds_read_b128 v[232:235], v159 offset:0
	ds_read_b128 v[236:239], v159 offset:8192
	s_waitcnt lgkmcnt(2)
	v_mfma_f32_32x32x16_bf16 v[64:79], v[224:227], v[120:123], v[64:79]
	v_mfma_f32_32x32x16_bf16 v[80:95], v[228:231], v[120:123], v[80:95]
	ds_read_b128 v[252:255], v248 offset:0
	ds_read_b128 v[240:243], v160 offset:16384
	ds_read_b128 v[244:247], v160 offset:20480
	s_waitcnt lgkmcnt(3)
	v_mfma_f32_32x32x16_bf16 v[64:79], v[232:235], v[124:127], v[64:79]
	v_mfma_f32_32x32x16_bf16 v[80:95], v[236:239], v[124:127], v[80:95]
	ds_read_b128 v[144:147], v248 offset:1024
	ds_read_b128 v[224:227], v161 offset:16384
	ds_read_b128 v[228:231], v161 offset:20480
	s_waitcnt lgkmcnt(3)
	v_mfma_f32_32x32x16_bf16 v[64:79], v[240:243], v[252:255], v[64:79]
	v_mfma_f32_32x32x16_bf16 v[80:95], v[244:247], v[252:255], v[80:95]
	ds_read_b128 v[148:151], v248 offset:2048
	ds_read_b128 v[232:235], v162 offset:16384
	ds_read_b128 v[236:239], v162 offset:20480
	s_waitcnt lgkmcnt(3)
	v_mfma_f32_32x32x16_bf16 v[64:79], v[224:227], v[144:147], v[64:79]
	v_mfma_f32_32x32x16_bf16 v[80:95], v[228:231], v[144:147], v[80:95]
	ds_read_b128 v[252:255], v248 offset:3072
	ds_read_b128 v[240:243], v163 offset:16384
	ds_read_b128 v[244:247], v163 offset:20480
	s_waitcnt lgkmcnt(3)
	v_mfma_f32_32x32x16_bf16 v[64:79], v[232:235], v[148:151], v[64:79]
	v_mfma_f32_32x32x16_bf16 v[80:95], v[236:239], v[148:151], v[80:95]
	s_waitcnt lgkmcnt(0)
	v_mfma_f32_32x32x16_bf16 v[64:79], v[240:243], v[252:255], v[64:79]
	v_mfma_f32_32x32x16_bf16 v[80:95], v[244:247], v[252:255], v[80:95]
	s_nop 11
	v_max3_f32 v224, v64, v65, v66
	v_max3_f32 v225, v80, v81, v82
	v_max3_f32 v224, v224, v67, v68
	v_max3_f32 v225, v225, v83, v84
	v_max3_f32 v224, v224, v69, v70
	v_max3_f32 v225, v225, v85, v86
	v_max3_f32 v224, v224, v71, v72
	v_max3_f32 v225, v225, v87, v88
	v_max3_f32 v224, v224, v73, v74
	v_max3_f32 v225, v225, v89, v90
	v_max3_f32 v224, v224, v75, v76
	v_max3_f32 v225, v225, v91, v92
	v_max3_f32 v224, v224, v77, v78
	v_max3_f32 v225, v225, v93, v94
	v_max_f32_e32 v224, v79, v224
	v_max_f32_e32 v225, v95, v225
	v_max_f32_e32 v226, v224, v225
	v_mov_b32_e32 v227, v226
	s_nop 1
	v_permlane32_swap_b32_e32 v226, v227
	v_max_f32_e32 v226, v226, v227
	v_sub_f32_e32 v208, 0, v226
	v_sub_f32_e32 v209, 0, v226
	v_sub_f32_e32 v210, 0, v226
	v_sub_f32_e32 v211, 0, v226
	v_sub_f32_e32 v212, 0, v226
	v_sub_f32_e32 v213, 0, v226
	v_sub_f32_e32 v214, 0, v226
	v_sub_f32_e32 v215, 0, v226
	v_sub_f32_e32 v216, 0, v226
	v_sub_f32_e32 v217, 0, v226
	v_sub_f32_e32 v218, 0, v226
	v_sub_f32_e32 v219, 0, v226
	v_sub_f32_e32 v220, 0, v226
	v_sub_f32_e32 v221, 0, v226
	v_sub_f32_e32 v222, 0, v226
	v_sub_f32_e32 v223, 0, v226
	v_sub_f32_e32 v64, v64, v226
	v_sub_f32_e32 v65, v65, v226
	v_sub_f32_e32 v66, v66, v226
	v_sub_f32_e32 v67, v67, v226
	v_sub_f32_e32 v68, v68, v226
	v_sub_f32_e32 v69, v69, v226
	v_sub_f32_e32 v70, v70, v226
	v_sub_f32_e32 v71, v71, v226
	v_sub_f32_e32 v72, v72, v226
	v_sub_f32_e32 v73, v73, v226
	v_sub_f32_e32 v74, v74, v226
	v_sub_f32_e32 v75, v75, v226
	v_sub_f32_e32 v76, v76, v226
	v_sub_f32_e32 v77, v77, v226
	v_sub_f32_e32 v78, v78, v226
	v_sub_f32_e32 v79, v79, v226
	v_sub_f32_e32 v80, v80, v226
	v_sub_f32_e32 v81, v81, v226
	v_sub_f32_e32 v82, v82, v226
	v_sub_f32_e32 v83, v83, v226
	v_sub_f32_e32 v84, v84, v226
	v_sub_f32_e32 v85, v85, v226
	v_sub_f32_e32 v86, v86, v226
	v_sub_f32_e32 v87, v87, v226
	v_sub_f32_e32 v88, v88, v226
	v_sub_f32_e32 v89, v89, v226
	v_sub_f32_e32 v90, v90, v226
	v_sub_f32_e32 v91, v91, v226
	v_sub_f32_e32 v92, v92, v226
	v_sub_f32_e32 v93, v93, v226
	v_sub_f32_e32 v94, v94, v226
	v_sub_f32_e32 v95, v95, v226
	v_exp_f32_e32 v64, v64
	v_exp_f32_e32 v65, v65
	v_exp_f32_e32 v66, v66
	v_exp_f32_e32 v67, v67
	v_exp_f32_e32 v68, v68
	v_exp_f32_e32 v69, v69
	v_exp_f32_e32 v70, v70
	v_exp_f32_e32 v71, v71
	v_exp_f32_e32 v72, v72
	v_exp_f32_e32 v73, v73
	v_exp_f32_e32 v74, v74
	v_exp_f32_e32 v75, v75
	v_exp_f32_e32 v76, v76
	v_exp_f32_e32 v77, v77
	v_exp_f32_e32 v78, v78
	v_exp_f32_e32 v79, v79
	s_waitcnt vmcnt(0) lgkmcnt(0)
	s_barrier
; __device__ __forceinline__ void finishSM(f32x16& p0, f32x16& p1, float alpha, float& l_reg, bf16x8& pa0, bf16x8& pa1, bf16x8& pa2, bf16x8& pa3) {
; #pragma unroll
;   for (int r = 0; r < 16; ++r) p1[r] = __builtin_amdgcn_exp2f(p1[r]);
;   float ps = 0;
; #pragma unroll
;   for (int r = 0; r < 16; ++r) ps += p0[r];
; #pragma unroll
;   for (int r = 0; r < 16; ++r) ps += p1[r];
;   { auto rr = __builtin_amdgcn_permlane32_swap(__float_as_uint(ps), __float_as_uint(ps), false, false);
;     ps = __uint_as_float(rr[0]) + __uint_as_float(rr[1]); }
;   l_reg = l_reg * alpha + ps;
;     ...
;   PK4(p0, 0, pa0); PK4(p0, 8, pa1); PK4(p1, 0, pa2); PK4(p1, 8, pa3);
;     ...
; }
; template <int DN>
; __device__ __forceinline__ void qkt(f32x16& p0, f32x16& p1, const char* Kn, const char* Kr, const bf16x8* qr, const char* qrl, int r32, int hi) {
;   p0 = f32x16{}; p1 = f32x16{};
;   if constexpr (DN > 0) {
; #pragma unroll
;     for (int d0 = 0; d0 < DN / 16; ++d0) { const int cb = (d0 * 16 + hi * 8) * 2;
;       bf16x8 b0 = *reinterpret_cast<const bf16x8*>(Kn + KSWZ(r32, cb));
;       bf16x8 b1 = *reinterpret_cast<const bf16x8*>(Kn + KSWZ(32 + r32, cb));
;       p0 = __builtin_amdgcn_mfma_f32_32x32x16_bf16(b0, qr[d0], p0, 0, 0, 0);
;       p1 = __builtin_amdgcn_mfma_f32_32x32x16_bf16(b1, qr[d0], p1, 0, 0, 0); }
;   }
; #pragma unroll
;   for (int d0 = 0; d0 < 4; ++d0) { const int cb = (d0 * 16 + hi * 8) * 2;
;     bf16x8 b0 = *reinterpret_cast<const bf16x8*>(Kr + KSWZ64(r32, cb));
;     bf16x8 b1 = *reinterpret_cast<const bf16x8*>(Kr + KSWZ64(32 + r32, cb));
;     bf16x8 q; if constexpr (DN > 0) q = *reinterpret_cast<const bf16x8*>(qrl + d0 * 1024); else q = qr[d0];
;     p0 = __builtin_amdgcn_mfma_f32_32x32x16_bf16(b0, q, p0, 0, 0, 0);
;     p1 = __builtin_amdgcn_mfma_f32_32x32x16_bf16(b1, q, p1, 0, 0, 0); }
; }
	ds_read_b128 v[224:227], v152 offset:24576
	ds_read_b128 v[228:231], v152 offset:32768
	ds_read_b128 v[232:235], v153 offset:24576
	ds_read_b128 v[236:239], v153 offset:32768
	s_add_i32 m0, s82, 65536
	s_nop 0
	global_load_lds_dwordx4 v165, s[4:5]
	s_add_i32 m0, s82, 66560
	s_nop 0
	global_load_lds_dwordx4 v169, s[4:5]
	s_add_i32 m0, s82, 0
	s_nop 0
	global_load_lds_dwordx4 v166, s[6:7]
	s_add_i32 m0, s82, 1024
	s_nop 0
	global_load_lds_dwordx4 v167, s[6:7]
	s_add_i32 m0, s83, 16384
	s_nop 0
	global_load_lds_dwordx4 v168, s[8:9]
	s_mov_b64 s[4:5], s[6:7]
	s_add_u32 s6, s6, 0x80000
	s_addc_u32 s7, s7, 0
	s_add_u32 s8, s8, 0x2000
	s_addc_u32 s9, s9, 0
	v_exp_f32_e32 v80, v80
	v_exp_f32_e32 v81, v81
	v_exp_f32_e32 v82, v82
	v_exp_f32_e32 v83, v83
	v_exp_f32_e32 v84, v84
	v_exp_f32_e32 v85, v85
	v_exp_f32_e32 v86, v86
	v_exp_f32_e32 v87, v87
	v_exp_f32_e32 v88, v88
	v_exp_f32_e32 v89, v89
	v_exp_f32_e32 v90, v90
	v_exp_f32_e32 v91, v91
	v_exp_f32_e32 v92, v92
	v_exp_f32_e32 v93, v93
	v_exp_f32_e32 v94, v94
	v_exp_f32_e32 v95, v95
	s_waitcnt lgkmcnt(2)
	v_mfma_f32_32x32x16_bf16 v[176:191], v[224:227], v[96:99], v[208:223]
	v_add_f32_e32 v170, v64, v170
	v_cvt_pk_bf16_f32 v128, v64, v65
	v_mfma_f32_32x32x16_bf16 v[192:207], v[228:231], v[96:99], v[208:223]
	ds_read_b128 v[240:243], v154 offset:24576
	ds_read_b128 v[244:247], v154 offset:32768
	v_add_f32_e32 v170, v65, v170
	v_cvt_pk_bf16_f32 v129, v66, v67
	v_add_f32_e32 v170, v66, v170
	s_waitcnt lgkmcnt(2)
	v_mfma_f32_32x32x16_bf16 v[176:191], v[232:235], v[100:103], v[176:191]
	v_cvt_pk_bf16_f32 v130, v68, v69
	v_add_f32_e32 v170, v67, v170
	v_mfma_f32_32x32x16_bf16 v[192:207], v[236:239], v[100:103], v[192:207]
	ds_read_b128 v[224:227], v155 offset:24576
	ds_read_b128 v[228:231], v155 offset:32768
	v_cvt_pk_bf16_f32 v131, v70, v71
	v_add_f32_e32 v170, v68, v170
	v_add_f32_e32 v170, v69, v170
	s_waitcnt lgkmcnt(2)
	v_mfma_f32_32x32x16_bf16 v[176:191], v[240:243], v[104:107], v[176:191]
	v_add_f32_e32 v170, v70, v170
	v_add_f32_e32 v170, v71, v170
	v_mfma_f32_32x32x16_bf16 v[192:207], v[244:247], v[104:107], v[192:207]
	ds_read_b128 v[232:235], v156 offset:24576
	ds_read_b128 v[236:239], v156 offset:32768
	v_add_f32_e32 v170, v72, v170
	v_cvt_pk_bf16_f32 v132, v72, v73
	v_add_f32_e32 v170, v73, v170
	s_waitcnt lgkmcnt(2)
	v_mfma_f32_32x32x16_bf16 v[176:191], v[224:227], v[108:111], v[176:191]
	v_cvt_pk_bf16_f32 v133, v74, v75
	v_add_f32_e32 v170, v74, v170
	v_mfma_f32_32x32x16_bf16 v[192:207], v[228:231], v[108:111], v[192:207]
	ds_read_b128 v[240:243], v157 offset:24576
	ds_read_b128 v[244:247], v157 offset:32768
	v_cvt_pk_bf16_f32 v134, v76, v77
	v_add_f32_e32 v170, v75, v170
	v_cvt_pk_bf16_f32 v135, v78, v79
	s_waitcnt lgkmcnt(2)
	v_mfma_f32_32x32x16_bf16 v[176:191], v[232:235], v[112:115], v[176:191]
	v_add_f32_e32 v170, v76, v170
	v_add_f32_e32 v170, v77, v170
	v_mfma_f32_32x32x16_bf16 v[192:207], v[236:239], v[112:115], v[192:207]
	ds_read_b128 v[224:227], v158 offset:24576
	ds_read_b128 v[228:231], v158 offset:32768
	v_add_f32_e32 v170, v78, v170
	v_add_f32_e32 v170, v79, v170
	ds_read_b64_tr_b16 v[64:65], v164 offset:0
	ds_read_b64_tr_b16 v[66:67], v164 offset:2048
	ds_read_b64_tr_b16 v[68:69], v164 offset:4096
	ds_read_b64_tr_b16 v[70:71], v164 offset:6144
	s_waitcnt lgkmcnt(6)
	v_mfma_f32_32x32x16_bf16 v[176:191], v[240:243], v[116:119], v[176:191]
	v_add_f32_e32 v171, v80, v81
	v_permlane32_swap_b32_e32 v128, v130
	v_mfma_f32_32x32x16_bf16 v[192:207], v[244:247], v[116:119], v[192:207]
	ds_read_b128 v[232:235], v159 offset:24576
	ds_read_b128 v[236:239], v159 offset:32768
	v_add_f32_e32 v171, v82, v171
	v_permlane32_swap_b32_e32 v129, v131
	v_add_f32_e32 v171, v83, v171
	s_waitcnt lgkmcnt(6)
	v_mfma_f32_32x32x16_bf16 v[176:191], v[224:227], v[120:123], v[176:191]
	v_permlane32_swap_b32_e32 v132, v134
	v_add_f32_e32 v171, v84, v171
	v_permlane32_swap_b32_e32 v133, v135
	v_mfma_f32_32x32x16_bf16 v[192:207], v[228:231], v[120:123], v[192:207]
	ds_read_b128 v[252:255], v248 offset:0
	ds_read_b128 v[240:243], v160 offset:40960
	ds_read_b128 v[244:247], v160 offset:45056
	v_add_f32_e32 v171, v85, v171
	v_add_f32_e32 v171, v86, v171
	s_waitcnt lgkmcnt(3)
; #define SBAR() __builtin_amdgcn_sched_barrier(0)
; __device__ __forceinline__ void partialSM(f32x16& p0, f32x16& p1, float& m_reg, float& alpha, const float C, const float THRS) {
;   float pmax = p0[0];
; #pragma unroll
;   for (int r = 1; r < 16; ++r) pmax = fmaxf(pmax, p0[r]);
; #pragma unroll
;   for (int r = 0; r < 16; ++r) pmax = fmaxf(pmax, p1[r]);
;   { auto rr = __builtin_amdgcn_permlane32_swap(__float_as_uint(pmax), __float_as_uint(pmax), false, false);
;     pmax = fmaxf(__uint_as_float(rr[0]), __uint_as_float(rr[1])); }
;   float mn;
;   if (__builtin_expect(__all(pmax - m_reg <= THRS), 1)) { mn = m_reg; alpha = 1.f; }
;   else { mn = fmaxf(m_reg, pmax); alpha = __builtin_amdgcn_exp2f((m_reg - mn) * C); m_reg = mn; }
; template <int OFF> __device__ __forceinline__ s16x4 tr_read(int vb) {
;   s16x4 r; asm volatile("ds_read_b64_tr_b16 %0, %1 offset:%2" : "=&v"(r) : "v"(vb), "i"(OFF) : "memory"); return r;
; }
; template <int D0, int NCB> __device__ __forceinline__ void pv_one(f32x16& od, int vb, bf16x8 pa0, bf16x8 pa1, bf16x8 pa2, bf16x8 pa3) {
;   const s16x4 l0 = tr_read<v_rd_off<NCB>(D0, 0, 0)>(vb), h0 = tr_read<v_rd_off<NCB>(D0, 0, 1)>(vb), l1 = tr_read<v_rd_off<NCB>(D0, 1, 0)>(vb), h1 = tr_read<v_rd_off<NCB>(D0, 1, 1)>(vb);
;   const s16x4 l2 = tr_read<v_rd_off<NCB>(D0, 2, 0)>(vb), h2 = tr_read<v_rd_off<NCB>(D0, 2, 1)>(vb), l3 = tr_read<v_rd_off<NCB>(D0, 3, 0)>(vb), h3 = tr_read<v_rd_off<NCB>(D0, 3, 1)>(vb);
;   asm volatile("s_waitcnt lgkmcnt(0)" ::: "memory"); SBAR();
;     ...
;   od = __builtin_amdgcn_mfma_f32_32x32x16_bf16(pa0, PK(l0, h0), od, 0, 0, 0);
;   od = __builtin_amdgcn_mfma_f32_32x32x16_bf16(pa1, PK(l1, h1), od, 0, 0, 0);
;   od = __builtin_amdgcn_mfma_f32_32x32x16_bf16(pa2, PK(l2, h2), od, 0, 0, 0);
;   od = __builtin_amdgcn_mfma_f32_32x32x16_bf16(pa3, PK(l3, h3), od, 0, 0, 0);
;     ...
; }
; template <int NCB> __device__ __forceinline__ void pv_all(f32x16* o, int vb, bf16x8 pa0, bf16x8 pa1, bf16x8 pa2, bf16x8 pa3) {
;   pv_one<0, NCB>(o[0], vb, pa0, pa1, pa2, pa3); pv_one<1, NCB>(o[1], vb, pa0, pa1, pa2, pa3);
;   if constexpr (NCB == 4) { pv_one<2, NCB>(o[2], vb, pa0, pa1, pa2, pa3); pv_one<3, NCB>(o[3], vb, pa0, pa1, pa2, pa3); }
; }
	v_mfma_f32_32x32x16_bf16 v[176:191], v[232:235], v[124:127], v[176:191]
	v_add_f32_e32 v171, v87, v171
	v_add_f32_e32 v171, v88, v171
	ds_read_b64_tr_b16 v[72:73], v164 offset:8192
	ds_read_b64_tr_b16 v[74:75], v164 offset:10240
	ds_read_b64_tr_b16 v[76:77], v164 offset:12288
	ds_read_b64_tr_b16 v[78:79], v164 offset:14336
	v_mfma_f32_32x32x16_bf16 v[192:207], v[236:239], v[124:127], v[192:207]
	ds_read_b128 v[144:147], v248 offset:1024
	ds_read_b128 v[224:227], v161 offset:40960
	ds_read_b128 v[228:231], v161 offset:45056
	v_add_f32_e32 v171, v89, v171
	v_cvt_pk_bf16_f32 v136, v80, v81
	s_waitcnt lgkmcnt(7)
	v_mfma_f32_32x32x16_bf16 v[176:191], v[240:243], v[252:255], v[176:191]
	v_add_f32_e32 v171, v90, v171
	v_cvt_pk_bf16_f32 v137, v82, v83
	v_add_f32_e32 v171, v91, v171
	v_mfma_f32_32x32x16_bf16 v[192:207], v[244:247], v[252:255], v[192:207]
	ds_read_b128 v[148:151], v248 offset:2048
	ds_read_b128 v[232:235], v162 offset:40960
	ds_read_b128 v[236:239], v162 offset:45056
	v_cvt_pk_bf16_f32 v138, v84, v85
	v_add_f32_e32 v171, v92, v171
	s_waitcnt lgkmcnt(3)
	v_mfma_f32_32x32x16_bf16 v[176:191], v[224:227], v[144:147], v[176:191]
	v_cvt_pk_bf16_f32 v139, v86, v87
	v_add_f32_e32 v171, v93, v171
	v_cvt_pk_bf16_f32 v140, v88, v89
	v_mfma_f32_32x32x16_bf16 v[192:207], v[228:231], v[144:147], v[192:207]
	ds_read_b128 v[252:255], v248 offset:3072
	ds_read_b128 v[240:243], v163 offset:40960
	ds_read_b128 v[244:247], v163 offset:45056
	v_add_f32_e32 v171, v94, v171
	v_cvt_pk_bf16_f32 v141, v90, v91
	s_waitcnt lgkmcnt(3)
	v_mfma_f32_32x32x16_bf16 v[176:191], v[232:235], v[148:151], v[176:191]
	v_add_f32_e32 v171, v95, v171
	v_cvt_pk_bf16_f32 v142, v92, v93
	v_add_f32_e32 v170, v171, v170
	v_mfma_f32_32x32x16_bf16 v[192:207], v[236:239], v[148:151], v[192:207]
	v_cvt_pk_bf16_f32 v143, v94, v95
	s_nop 0
	s_waitcnt lgkmcnt(0)
	v_mfma_f32_32x32x16_bf16 v[176:191], v[240:243], v[252:255], v[176:191]
	v_permlane32_swap_b32_e32 v136, v138
	v_permlane32_swap_b32_e32 v137, v139
	v_permlane32_swap_b32_e32 v140, v142
	v_mfma_f32_32x32x16_bf16 v[192:207], v[244:247], v[252:255], v[192:207]
	v_permlane32_swap_b32_e32 v141, v143
	ds_read_b64_tr_b16 v[80:81], v164 offset:512
	ds_read_b64_tr_b16 v[82:83], v164 offset:2560
	ds_read_b64_tr_b16 v[84:85], v164 offset:4608
	ds_read_b64_tr_b16 v[86:87], v164 offset:6656
	ds_read_b64_tr_b16 v[88:89], v164 offset:8704
	ds_read_b64_tr_b16 v[90:91], v164 offset:10752
	ds_read_b64_tr_b16 v[92:93], v164 offset:12800
	ds_read_b64_tr_b16 v[94:95], v164 offset:14848
	s_waitcnt lgkmcnt(15)
	v_mfma_f32_32x32x16_bf16 v[0:15], v[128:131], v[64:67], v[0:15]
	v_mfma_f32_32x32x16_bf16 v[0:15], v[132:135], v[68:71], v[0:15]
	ds_read_b64_tr_b16 v[64:65], v164 offset:1024
	ds_read_b64_tr_b16 v[66:67], v164 offset:3072
	ds_read_b64_tr_b16 v[68:69], v164 offset:5120
	ds_read_b64_tr_b16 v[70:71], v164 offset:7168
	v_mfma_f32_32x32x16_bf16 v[0:15], v[136:139], v[72:75], v[0:15]
	v_mfma_f32_32x32x16_bf16 v[0:15], v[140:143], v[76:79], v[0:15]
	ds_read_b64_tr_b16 v[72:73], v164 offset:9216
	ds_read_b64_tr_b16 v[74:75], v164 offset:11264
	ds_read_b64_tr_b16 v[76:77], v164 offset:13312
	ds_read_b64_tr_b16 v[78:79], v164 offset:15360
	s_waitcnt lgkmcnt(8)
	v_mfma_f32_32x32x16_bf16 v[48:63], v[128:131], v[80:83], v[48:63]
	v_max3_f32 v224, v176, v177, v178
	v_max3_f32 v225, v192, v193, v194
	v_max3_f32 v224, v224, v179, v180
	v_max3_f32 v225, v225, v195, v196
	v_max3_f32 v224, v224, v181, v182
	v_mfma_f32_32x32x16_bf16 v[48:63], v[132:135], v[84:87], v[48:63]
	v_max3_f32 v225, v225, v197, v198
	v_max3_f32 v224, v224, v183, v184
	v_max3_f32 v225, v225, v199, v200
	v_max3_f32 v224, v224, v185, v186
	v_max3_f32 v225, v225, v201, v202
	ds_read_b64_tr_b16 v[80:81], v164 offset:1536
	ds_read_b64_tr_b16 v[82:83], v164 offset:3584
	ds_read_b64_tr_b16 v[84:85], v164 offset:5632
	ds_read_b64_tr_b16 v[86:87], v164 offset:7680
	v_mfma_f32_32x32x16_bf16 v[48:63], v[136:139], v[88:91], v[48:63]
	v_max3_f32 v224, v224, v187, v188
	v_max3_f32 v225, v225, v203, v204
	v_max3_f32 v224, v224, v189, v190
	v_max3_f32 v225, v225, v205, v206
	v_max_f32_e32 v224, v191, v224
	v_mfma_f32_32x32x16_bf16 v[48:63], v[140:143], v[92:95], v[48:63]
	v_max_f32_e32 v225, v207, v225
	v_max_f32_e32 v226, v224, v225
	v_mov_b32_e32 v227, v226
	s_nop 1
	v_permlane32_swap_b32_e32 v226, v227
	v_max_f32_e32 v226, v226, v227
	ds_read_b64_tr_b16 v[88:89], v164 offset:9728
	ds_read_b64_tr_b16 v[90:91], v164 offset:11776
	ds_read_b64_tr_b16 v[92:93], v164 offset:13824
	ds_read_b64_tr_b16 v[94:95], v164 offset:15872
	s_waitcnt lgkmcnt(8)
	v_mfma_f32_32x32x16_bf16 v[32:47], v[128:131], v[64:67], v[32:47]
	v_cmp_lt_f32_e32 vcc, 0x4138aa3b, v226
	s_cbranch_vccnz .Lat_r1_s1

; #define SBAR() __builtin_amdgcn_sched_barrier(0)
; #define WAITV() asm volatile("s_waitcnt vmcnt(0)" ::: "memory")
; __device__ __forceinline__ void finishSM(f32x16& p0, f32x16& p1, float alpha, float& l_reg, bf16x8& pa0, bf16x8& pa1, bf16x8& pa2, bf16x8& pa3) {
; #pragma unroll
;   for (int r = 0; r < 16; ++r) p1[r] = __builtin_amdgcn_exp2f(p1[r]);
;   float ps = 0;
; #pragma unroll
;   for (int r = 0; r < 16; ++r) ps += p0[r];
; #pragma unroll
;   for (int r = 0; r < 16; ++r) ps += p1[r];
;   { auto rr = __builtin_amdgcn_permlane32_swap(__float_as_uint(ps), __float_as_uint(ps), false, false);
;     ps = __uint_as_float(rr[0]) + __uint_as_float(rr[1]); }
;   l_reg = l_reg * alpha + ps;
;     ...
;   PK4(p0, 0, pa0); PK4(p0, 8, pa1); PK4(p1, 0, pa2); PK4(p1, 8, pa3);
;     ...
; }
; template <int DN>
; __device__ __forceinline__ void qkt(f32x16& p0, f32x16& p1, const char* Kn, const char* Kr, const bf16x8* qr, const char* qrl, int r32, int hi) {
;   p0 = f32x16{}; p1 = f32x16{};
;   if constexpr (DN > 0) {
; #pragma unroll
;     for (int d0 = 0; d0 < DN / 16; ++d0) { const int cb = (d0 * 16 + hi * 8) * 2;
;       bf16x8 b0 = *reinterpret_cast<const bf16x8*>(Kn + KSWZ(r32, cb));
;       bf16x8 b1 = *reinterpret_cast<const bf16x8*>(Kn + KSWZ(32 + r32, cb));
;       p0 = __builtin_amdgcn_mfma_f32_32x32x16_bf16(b0, qr[d0], p0, 0, 0, 0);
;       p1 = __builtin_amdgcn_mfma_f32_32x32x16_bf16(b1, qr[d0], p1, 0, 0, 0); }
;   }
; #pragma unroll
;   for (int d0 = 0; d0 < 4; ++d0) { const int cb = (d0 * 16 + hi * 8) * 2;
;     bf16x8 b0 = *reinterpret_cast<const bf16x8*>(Kr + KSWZ64(r32, cb));
;     bf16x8 b1 = *reinterpret_cast<const bf16x8*>(Kr + KSWZ64(32 + r32, cb));
;     bf16x8 q; if constexpr (DN > 0) q = *reinterpret_cast<const bf16x8*>(qrl + d0 * 1024); else q = qr[d0];
;     p0 = __builtin_amdgcn_mfma_f32_32x32x16_bf16(b0, q, p0, 0, 0, 0);
;     p1 = __builtin_amdgcn_mfma_f32_32x32x16_bf16(b1, q, p1, 0, 0, 0); }
; }
; template <int DN, int DV, bool MASK> ...
;     ...
;   for (int j = 1; j + 1 < NT; j += 2) {
;     DMA(j + 1, bn);
;     nB = NEED(j);
;     SBAR(); if (nB) SCORE(pB0, pB1, bc, j);
;     if (nA) finishSM(pA0, pA1, alA, l_reg, pa0, pa1, pa2, pa3); SBAR();
;     if (nA) pv_all<NCB>(o, vb0 + bp, pa0, pa1, pa2, pa3);
;     if (nB) { partialSM(pB0, pB1, m_reg, alB, C, THRS); RESC(alB); }
;     WAITV(); __syncthreads(); ROT();
.Lat_loop:
	ds_read_b128 v[224:227], v152 offset:0
	ds_read_b128 v[228:231], v152 offset:8192
	ds_read_b128 v[232:235], v153 offset:0
	ds_read_b128 v[236:239], v153 offset:8192
	v_mfma_f32_32x32x16_bf16 v[16:31], v[128:131], v[80:83], v[16:31]
	s_add_i32 m0, s82, 49152
	v_exp_f32_e32 v192, v192
	global_load_lds_dwordx4 v165, s[4:5]
	v_exp_f32_e32 v193, v193
	s_add_i32 m0, s82, 50176
	v_exp_f32_e32 v194, v194
	global_load_lds_dwordx4 v169, s[4:5]
	v_mfma_f32_32x32x16_bf16 v[16:31], v[132:135], v[84:87], v[16:31]
	v_exp_f32_e32 v195, v195
	s_add_i32 m0, s82, 24576
	v_exp_f32_e32 v196, v196
	global_load_lds_dwordx4 v166, s[6:7]
	v_exp_f32_e32 v197, v197
	s_add_i32 m0, s82, 25600
	v_exp_f32_e32 v198, v198
	global_load_lds_dwordx4 v167, s[6:7]
	v_mfma_f32_32x32x16_bf16 v[16:31], v[136:139], v[88:91], v[16:31]
	v_exp_f32_e32 v199, v199
	s_add_i32 m0, s83, 40960
	v_exp_f32_e32 v200, v200
	global_load_lds_dwordx4 v168, s[8:9]
	v_exp_f32_e32 v201, v201
	s_mov_b64 s[4:5], s[6:7]
	v_exp_f32_e32 v202, v202
	s_add_u32 s6, s6, 0x80000
	v_mfma_f32_32x32x16_bf16 v[16:31], v[140:143], v[92:95], v[16:31]
	v_exp_f32_e32 v203, v203
	s_addc_u32 s7, s7, 0
	v_exp_f32_e32 v204, v204
	s_add_u32 s8, s8, 0x2000
	v_exp_f32_e32 v205, v205
	s_addc_u32 s9, s9, 0
	v_exp_f32_e32 v206, v206
	v_exp_f32_e32 v207, v207
	s_cmp_lg_u32 s10, 0
	s_cbranch_scc1 .Lat_r2_la
.Lat_r2ret_la:
	s_waitcnt lgkmcnt(2)
	v_mfma_f32_32x32x16_bf16 v[64:79], v[224:227], v[96:99], v[208:223]
	v_add_f32_e32 v170, v176, v170
	v_cvt_pk_bf16_f32 v128, v176, v177
	v_mfma_f32_32x32x16_bf16 v[80:95], v[228:231], v[96:99], v[208:223]
	ds_read_b128 v[240:243], v154 offset:0
	ds_read_b128 v[244:247], v154 offset:8192
	v_add_f32_e32 v170, v177, v170
	v_cvt_pk_bf16_f32 v129, v178, v179
	v_add_f32_e32 v170, v178, v170
	s_waitcnt lgkmcnt(2)
	v_mfma_f32_32x32x16_bf16 v[64:79], v[232:235], v[100:103], v[64:79]
	v_cvt_pk_bf16_f32 v130, v180, v181
	v_add_f32_e32 v170, v179, v170
	v_mfma_f32_32x32x16_bf16 v[80:95], v[236:239], v[100:103], v[80:95]
	ds_read_b128 v[224:227], v155 offset:0
	ds_read_b128 v[228:231], v155 offset:8192
	v_cvt_pk_bf16_f32 v131, v182, v183
	v_add_f32_e32 v170, v180, v170
	v_add_f32_e32 v170, v181, v170
	s_waitcnt lgkmcnt(2)
	v_mfma_f32_32x32x16_bf16 v[64:79], v[240:243], v[104:107], v[64:79]
	v_add_f32_e32 v170, v182, v170
	v_add_f32_e32 v170, v183, v170
	v_mfma_f32_32x32x16_bf16 v[80:95], v[244:247], v[104:107], v[80:95]
	ds_read_b128 v[232:235], v156 offset:0
	ds_read_b128 v[236:239], v156 offset:8192
	v_add_f32_e32 v170, v184, v170
	v_cvt_pk_bf16_f32 v132, v184, v185
	v_add_f32_e32 v170, v185, v170
	s_waitcnt lgkmcnt(2)
	v_mfma_f32_32x32x16_bf16 v[64:79], v[224:227], v[108:111], v[64:79]
	v_cvt_pk_bf16_f32 v133, v186, v187
	v_add_f32_e32 v170, v186, v170
	v_mfma_f32_32x32x16_bf16 v[80:95], v[228:231], v[108:111], v[80:95]
	ds_read_b128 v[240:243], v157 offset:0
	ds_read_b128 v[244:247], v157 offset:8192
	v_cvt_pk_bf16_f32 v134, v188, v189
	v_add_f32_e32 v170, v187, v170
	v_cvt_pk_bf16_f32 v135, v190, v191
	s_waitcnt lgkmcnt(2)
	v_mfma_f32_32x32x16_bf16 v[64:79], v[232:235], v[112:115], v[64:79]
	v_add_f32_e32 v170, v188, v170
	v_add_f32_e32 v170, v189, v170
	v_mfma_f32_32x32x16_bf16 v[80:95], v[236:239], v[112:115], v[80:95]
	ds_read_b128 v[224:227], v158 offset:0
	ds_read_b128 v[228:231], v158 offset:8192
	v_add_f32_e32 v170, v190, v170
	v_add_f32_e32 v170, v191, v170
	ds_read_b64_tr_b16 v[176:177], v164 offset:16384
	ds_read_b64_tr_b16 v[178:179], v164 offset:18432
	ds_read_b64_tr_b16 v[180:181], v164 offset:20480
	ds_read_b64_tr_b16 v[182:183], v164 offset:22528
	s_waitcnt lgkmcnt(6)
	v_mfma_f32_32x32x16_bf16 v[64:79], v[240:243], v[116:119], v[64:79]
	v_add_f32_e32 v171, v192, v193
	v_permlane32_swap_b32_e32 v128, v130
	v_mfma_f32_32x32x16_bf16 v[80:95], v[244:247], v[116:119], v[80:95]
	ds_read_b128 v[232:235], v159 offset:0
	ds_read_b128 v[236:239], v159 offset:8192
	v_add_f32_e32 v171, v194, v171
	v_permlane32_swap_b32_e32 v129, v131
	v_add_f32_e32 v171, v195, v171
	s_waitcnt lgkmcnt(6)
	v_mfma_f32_32x32x16_bf16 v[64:79], v[224:227], v[120:123], v[64:79]
	v_permlane32_swap_b32_e32 v132, v134
	v_add_f32_e32 v171, v196, v171
	v_permlane32_swap_b32_e32 v133, v135
	v_mfma_f32_32x32x16_bf16 v[80:95], v[228:231], v[120:123], v[80:95]
	ds_read_b128 v[252:255], v248 offset:0
	ds_read_b128 v[240:243], v160 offset:16384
	ds_read_b128 v[244:247], v160 offset:20480
	v_add_f32_e32 v171, v197, v171
	v_add_f32_e32 v171, v198, v171
	s_waitcnt lgkmcnt(3)
	v_mfma_f32_32x32x16_bf16 v[64:79], v[232:235], v[124:127], v[64:79]
	v_add_f32_e32 v171, v199, v171
	v_add_f32_e32 v171, v200, v171
	ds_read_b64_tr_b16 v[184:185], v164 offset:24576
	ds_read_b64_tr_b16 v[186:187], v164 offset:26624
	ds_read_b64_tr_b16 v[188:189], v164 offset:28672
	ds_read_b64_tr_b16 v[190:191], v164 offset:30720
	v_mfma_f32_32x32x16_bf16 v[80:95], v[236:239], v[124:127], v[80:95]
	ds_read_b128 v[144:147], v248 offset:1024
	ds_read_b128 v[224:227], v161 offset:16384
	ds_read_b128 v[228:231], v161 offset:20480
	v_add_f32_e32 v171, v201, v171
	v_cvt_pk_bf16_f32 v136, v192, v193
	s_waitcnt lgkmcnt(7)
	v_mfma_f32_32x32x16_bf16 v[64:79], v[240:243], v[252:255], v[64:79]
	v_add_f32_e32 v171, v202, v171
	v_cvt_pk_bf16_f32 v137, v194, v195
	v_add_f32_e32 v171, v203, v171
	v_mfma_f32_32x32x16_bf16 v[80:95], v[244:247], v[252:255], v[80:95]
	ds_read_b128 v[148:151], v248 offset:2048
	ds_read_b128 v[232:235], v162 offset:16384
	ds_read_b128 v[236:239], v162 offset:20480
	v_cvt_pk_bf16_f32 v138, v196, v197
	v_add_f32_e32 v171, v204, v171
	s_waitcnt lgkmcnt(3)
; #define SBAR() __builtin_amdgcn_sched_barrier(0)
; #define WAITV() asm volatile("s_waitcnt vmcnt(0)" ::: "memory")
; #define NEED(j) (!MASK || (j) < n1 || (KP(j) <= q0w + 159 && KP(j) + 63 >= q0w - 128))
; #define SCORE(P0, P1, b, j) do { qkt<DN>(P0, P1, Knl + (b), Krl + (b), qr, qrl, r32, hi); \
;     if constexpr (MASK) { if ((j) >= n1 && !(KP(j) >= q0w - 97 && KP(j) <= q0w + 65)) band_mask(P0, P1, qd - KP(j)); } } while (0)
; #define ROT() do { const int t_ = bp; bp = bc; bc = bn; bn = t_; } while (0)
; template <int OFF> __device__ __forceinline__ s16x4 tr_read(int vb) {
;   s16x4 r; asm volatile("ds_read_b64_tr_b16 %0, %1 offset:%2" : "=&v"(r) : "v"(vb), "i"(OFF) : "memory"); return r;
; }
; template <int D0, int NCB> __device__ __forceinline__ void pv_one(f32x16& od, int vb, bf16x8 pa0, bf16x8 pa1, bf16x8 pa2, bf16x8 pa3) {
;   const s16x4 l0 = tr_read<v_rd_off<NCB>(D0, 0, 0)>(vb), h0 = tr_read<v_rd_off<NCB>(D0, 0, 1)>(vb), l1 = tr_read<v_rd_off<NCB>(D0, 1, 0)>(vb), h1 = tr_read<v_rd_off<NCB>(D0, 1, 1)>(vb);
;   const s16x4 l2 = tr_read<v_rd_off<NCB>(D0, 2, 0)>(vb), h2 = tr_read<v_rd_off<NCB>(D0, 2, 1)>(vb), l3 = tr_read<v_rd_off<NCB>(D0, 3, 0)>(vb), h3 = tr_read<v_rd_off<NCB>(D0, 3, 1)>(vb);
;   asm volatile("s_waitcnt lgkmcnt(0)" ::: "memory"); SBAR();
;     ...
;   od = __builtin_amdgcn_mfma_f32_32x32x16_bf16(pa0, PK(l0, h0), od, 0, 0, 0);
;   od = __builtin_amdgcn_mfma_f32_32x32x16_bf16(pa1, PK(l1, h1), od, 0, 0, 0);
;   od = __builtin_amdgcn_mfma_f32_32x32x16_bf16(pa2, PK(l2, h2), od, 0, 0, 0);
;   od = __builtin_amdgcn_mfma_f32_32x32x16_bf16(pa3, PK(l3, h3), od, 0, 0, 0);
;     ...
; }
; template <int NCB> __device__ __forceinline__ void pv_all(f32x16* o, int vb, bf16x8 pa0, bf16x8 pa1, bf16x8 pa2, bf16x8 pa3) {
;   pv_one<0, NCB>(o[0], vb, pa0, pa1, pa2, pa3); pv_one<1, NCB>(o[1], vb, pa0, pa1, pa2, pa3);
;   if constexpr (NCB == 4) { pv_one<2, NCB>(o[2], vb, pa0, pa1, pa2, pa3); pv_one<3, NCB>(o[3], vb, pa0, pa1, pa2, pa3); }
; }
; template <int DN, int DV, bool MASK> ...
;     ...
;     WAITV(); __syncthreads(); ROT();
;     DMA(j + 2, bn);
;     nA = NEED(j + 1);
;     SBAR(); if (nA) SCORE(pA0, pA1, bc, j + 1);
	v_mfma_f32_32x32x16_bf16 v[64:79], v[224:227], v[144:147], v[64:79]
	v_cvt_pk_bf16_f32 v139, v198, v199
	v_add_f32_e32 v171, v205, v171
	v_cvt_pk_bf16_f32 v140, v200, v201
	v_mfma_f32_32x32x16_bf16 v[80:95], v[228:231], v[144:147], v[80:95]
	ds_read_b128 v[252:255], v248 offset:3072
	ds_read_b128 v[240:243], v163 offset:16384
	ds_read_b128 v[244:247], v163 offset:20480
	v_add_f32_e32 v171, v206, v171
	v_cvt_pk_bf16_f32 v141, v202, v203
	s_waitcnt lgkmcnt(3)
	v_mfma_f32_32x32x16_bf16 v[64:79], v[232:235], v[148:151], v[64:79]
	v_add_f32_e32 v171, v207, v171
	v_cvt_pk_bf16_f32 v142, v204, v205
	v_add_f32_e32 v170, v171, v170
	v_mfma_f32_32x32x16_bf16 v[80:95], v[236:239], v[148:151], v[80:95]
	v_cvt_pk_bf16_f32 v143, v206, v207
	s_nop 0
	s_waitcnt lgkmcnt(0)
	v_mfma_f32_32x32x16_bf16 v[64:79], v[240:243], v[252:255], v[64:79]
	v_permlane32_swap_b32_e32 v136, v138
	v_permlane32_swap_b32_e32 v137, v139
	v_permlane32_swap_b32_e32 v140, v142
	v_mfma_f32_32x32x16_bf16 v[80:95], v[244:247], v[252:255], v[80:95]
	v_permlane32_swap_b32_e32 v141, v143
	ds_read_b64_tr_b16 v[192:193], v164 offset:16896
	ds_read_b64_tr_b16 v[194:195], v164 offset:18944
	ds_read_b64_tr_b16 v[196:197], v164 offset:20992
	ds_read_b64_tr_b16 v[198:199], v164 offset:23040
	ds_read_b64_tr_b16 v[200:201], v164 offset:25088
	ds_read_b64_tr_b16 v[202:203], v164 offset:27136
	ds_read_b64_tr_b16 v[204:205], v164 offset:29184
	ds_read_b64_tr_b16 v[206:207], v164 offset:31232
	s_waitcnt lgkmcnt(15)
	v_mfma_f32_32x32x16_bf16 v[0:15], v[128:131], v[176:179], v[0:15]
	v_mfma_f32_32x32x16_bf16 v[0:15], v[132:135], v[180:183], v[0:15]
	ds_read_b64_tr_b16 v[176:177], v164 offset:17408
	ds_read_b64_tr_b16 v[178:179], v164 offset:19456
	ds_read_b64_tr_b16 v[180:181], v164 offset:21504
	ds_read_b64_tr_b16 v[182:183], v164 offset:23552
	v_mfma_f32_32x32x16_bf16 v[0:15], v[136:139], v[184:187], v[0:15]
	v_mfma_f32_32x32x16_bf16 v[0:15], v[140:143], v[188:191], v[0:15]
	ds_read_b64_tr_b16 v[184:185], v164 offset:25600
	ds_read_b64_tr_b16 v[186:187], v164 offset:27648
	ds_read_b64_tr_b16 v[188:189], v164 offset:29696
	ds_read_b64_tr_b16 v[190:191], v164 offset:31744
	s_waitcnt lgkmcnt(8)
	v_mfma_f32_32x32x16_bf16 v[48:63], v[128:131], v[192:195], v[48:63]
	v_max3_f32 v224, v64, v65, v66
	v_max3_f32 v225, v80, v81, v82
	v_max3_f32 v224, v224, v67, v68
	v_max3_f32 v225, v225, v83, v84
	v_max3_f32 v224, v224, v69, v70
	v_mfma_f32_32x32x16_bf16 v[48:63], v[132:135], v[196:199], v[48:63]
	v_max3_f32 v225, v225, v85, v86
	v_max3_f32 v224, v224, v71, v72
	v_max3_f32 v225, v225, v87, v88
	v_max3_f32 v224, v224, v73, v74
	v_max3_f32 v225, v225, v89, v90
	ds_read_b64_tr_b16 v[192:193], v164 offset:17920
	ds_read_b64_tr_b16 v[194:195], v164 offset:19968
	ds_read_b64_tr_b16 v[196:197], v164 offset:22016
	ds_read_b64_tr_b16 v[198:199], v164 offset:24064
	v_mfma_f32_32x32x16_bf16 v[48:63], v[136:139], v[200:203], v[48:63]
	v_max3_f32 v224, v224, v75, v76
	v_max3_f32 v225, v225, v91, v92
	v_max3_f32 v224, v224, v77, v78
	v_max3_f32 v225, v225, v93, v94
	v_max_f32_e32 v224, v79, v224
	v_mfma_f32_32x32x16_bf16 v[48:63], v[140:143], v[204:207], v[48:63]
	v_max_f32_e32 v225, v95, v225
	v_max_f32_e32 v226, v224, v225
	v_mov_b32_e32 v227, v226
	s_nop 1
	v_permlane32_swap_b32_e32 v226, v227
	v_max_f32_e32 v226, v226, v227
	ds_read_b64_tr_b16 v[200:201], v164 offset:26112
	ds_read_b64_tr_b16 v[202:203], v164 offset:28160
	ds_read_b64_tr_b16 v[204:205], v164 offset:30208
	ds_read_b64_tr_b16 v[206:207], v164 offset:32256
	s_waitcnt lgkmcnt(8)
	v_mfma_f32_32x32x16_bf16 v[32:47], v[128:131], v[176:179], v[32:47]
	v_cmp_lt_f32_e32 vcc, 0x4138aa3b, v226
	s_cbranch_vccnz .Lat_r1_la
.Lat_r1ret_la:
	v_exp_f32_e32 v64, v64
	v_exp_f32_e32 v65, v65
	v_exp_f32_e32 v66, v66
	v_mfma_f32_32x32x16_bf16 v[32:47], v[132:135], v[180:183], v[32:47]
	v_exp_f32_e32 v67, v67
	v_exp_f32_e32 v68, v68
	v_exp_f32_e32 v69, v69
	v_exp_f32_e32 v70, v70
	v_mfma_f32_32x32x16_bf16 v[32:47], v[136:139], v[184:187], v[32:47]
	v_exp_f32_e32 v71, v71
	v_exp_f32_e32 v72, v72
	v_exp_f32_e32 v73, v73
	v_exp_f32_e32 v74, v74
	v_mfma_f32_32x32x16_bf16 v[32:47], v[140:143], v[188:191], v[32:47]
	v_exp_f32_e32 v75, v75
	v_exp_f32_e32 v76, v76
	v_exp_f32_e32 v77, v77
	v_exp_f32_e32 v78, v78
	v_exp_f32_e32 v79, v79
	s_waitcnt vmcnt(0) lgkmcnt(0)
	s_barrier
	ds_read_b128 v[224:227], v152 offset:24576
	ds_read_b128 v[228:231], v152 offset:32768
	ds_read_b128 v[232:235], v153 offset:24576
	ds_read_b128 v[236:239], v153 offset:32768
	v_mfma_f32_32x32x16_bf16 v[16:31], v[128:131], v[192:195], v[16:31]
	s_add_i32 m0, s82, 65536
	v_exp_f32_e32 v80, v80
	global_load_lds_dwordx4 v165, s[4:5]
	v_exp_f32_e32 v81, v81
	s_add_i32 m0, s82, 66560
	v_exp_f32_e32 v82, v82
	global_load_lds_dwordx4 v169, s[4:5]
	v_mfma_f32_32x32x16_bf16 v[16:31], v[132:135], v[196:199], v[16:31]
	v_exp_f32_e32 v83, v83
	s_add_i32 m0, s82, 0
	v_exp_f32_e32 v84, v84
	global_load_lds_dwordx4 v166, s[6:7]
	v_exp_f32_e32 v85, v85
	s_add_i32 m0, s82, 1024
	v_exp_f32_e32 v86, v86
	global_load_lds_dwordx4 v167, s[6:7]
	v_mfma_f32_32x32x16_bf16 v[16:31], v[136:139], v[200:203], v[16:31]
	v_exp_f32_e32 v87, v87
	s_add_i32 m0, s83, 16384
	v_exp_f32_e32 v88, v88
	global_load_lds_dwordx4 v168, s[8:9]
	v_exp_f32_e32 v89, v89
	s_mov_b64 s[4:5], s[6:7]
	v_exp_f32_e32 v90, v90
	s_add_u32 s6, s6, 0x80000
	v_mfma_f32_32x32x16_bf16 v[16:31], v[140:143], v[204:207], v[16:31]
	v_exp_f32_e32 v91, v91
	s_addc_u32 s7, s7, 0
	v_exp_f32_e32 v92, v92
	s_add_u32 s8, s8, 0x2000
	v_exp_f32_e32 v93, v93
	s_addc_u32 s9, s9, 0
	v_exp_f32_e32 v94, v94
	v_exp_f32_e32 v95, v95
	s_cmp_lg_u32 s10, 0
	s_cbranch_scc1 .Lat_r2_lb
; __device__ __forceinline__ void finishSM(f32x16& p0, f32x16& p1, float alpha, float& l_reg, bf16x8& pa0, bf16x8& pa1, bf16x8& pa2, bf16x8& pa3) {
; #pragma unroll
;   for (int r = 0; r < 16; ++r) p1[r] = __builtin_amdgcn_exp2f(p1[r]);
;   float ps = 0;
; #pragma unroll
;   for (int r = 0; r < 16; ++r) ps += p0[r];
; #pragma unroll
;   for (int r = 0; r < 16; ++r) ps += p1[r];
;   { auto rr = __builtin_amdgcn_permlane32_swap(__float_as_uint(ps), __float_as_uint(ps), false, false);
;     ps = __uint_as_float(rr[0]) + __uint_as_float(rr[1]); }
;   l_reg = l_reg * alpha + ps;
;     ...
;   PK4(p0, 0, pa0); PK4(p0, 8, pa1); PK4(p1, 0, pa2); PK4(p1, 8, pa3);
;     ...
; }
; template <int DN>
; __device__ __forceinline__ void qkt(f32x16& p0, f32x16& p1, const char* Kn, const char* Kr, const bf16x8* qr, const char* qrl, int r32, int hi) {
;   p0 = f32x16{}; p1 = f32x16{};
;   if constexpr (DN > 0) {
; #pragma unroll
;     for (int d0 = 0; d0 < DN / 16; ++d0) { const int cb = (d0 * 16 + hi * 8) * 2;
;       bf16x8 b0 = *reinterpret_cast<const bf16x8*>(Kn + KSWZ(r32, cb));
;       bf16x8 b1 = *reinterpret_cast<const bf16x8*>(Kn + KSWZ(32 + r32, cb));
;       p0 = __builtin_amdgcn_mfma_f32_32x32x16_bf16(b0, qr[d0], p0, 0, 0, 0);
;       p1 = __builtin_amdgcn_mfma_f32_32x32x16_bf16(b1, qr[d0], p1, 0, 0, 0); }
;   }
; #pragma unroll
;   for (int d0 = 0; d0 < 4; ++d0) { const int cb = (d0 * 16 + hi * 8) * 2;
;     bf16x8 b0 = *reinterpret_cast<const bf16x8*>(Kr + KSWZ64(r32, cb));
;     bf16x8 b1 = *reinterpret_cast<const bf16x8*>(Kr + KSWZ64(32 + r32, cb));
;     bf16x8 q; if constexpr (DN > 0) q = *reinterpret_cast<const bf16x8*>(qrl + d0 * 1024); else q = qr[d0];
;     p0 = __builtin_amdgcn_mfma_f32_32x32x16_bf16(b0, q, p0, 0, 0, 0);
;     p1 = __builtin_amdgcn_mfma_f32_32x32x16_bf16(b1, q, p1, 0, 0, 0); }
; }
.Lat_r2ret_lb:
	s_waitcnt lgkmcnt(2)
	v_mfma_f32_32x32x16_bf16 v[176:191], v[224:227], v[96:99], v[208:223]
	v_add_f32_e32 v170, v64, v170
	v_cvt_pk_bf16_f32 v128, v64, v65
	v_mfma_f32_32x32x16_bf16 v[192:207], v[228:231], v[96:99], v[208:223]
	ds_read_b128 v[240:243], v154 offset:24576
	ds_read_b128 v[244:247], v154 offset:32768
	v_add_f32_e32 v170, v65, v170
	v_cvt_pk_bf16_f32 v129, v66, v67
	v_add_f32_e32 v170, v66, v170
	s_waitcnt lgkmcnt(2)
	v_mfma_f32_32x32x16_bf16 v[176:191], v[232:235], v[100:103], v[176:191]
	v_cvt_pk_bf16_f32 v130, v68, v69
	v_add_f32_e32 v170, v67, v170
	v_mfma_f32_32x32x16_bf16 v[192:207], v[236:239], v[100:103], v[192:207]
	ds_read_b128 v[224:227], v155 offset:24576
	ds_read_b128 v[228:231], v155 offset:32768
	v_cvt_pk_bf16_f32 v131, v70, v71
	v_add_f32_e32 v170, v68, v170
	v_add_f32_e32 v170, v69, v170
	s_waitcnt lgkmcnt(2)
	v_mfma_f32_32x32x16_bf16 v[176:191], v[240:243], v[104:107], v[176:191]
	v_add_f32_e32 v170, v70, v170
	v_add_f32_e32 v170, v71, v170
	v_mfma_f32_32x32x16_bf16 v[192:207], v[244:247], v[104:107], v[192:207]
	ds_read_b128 v[232:235], v156 offset:24576
	ds_read_b128 v[236:239], v156 offset:32768
	v_add_f32_e32 v170, v72, v170
	v_cvt_pk_bf16_f32 v132, v72, v73
	v_add_f32_e32 v170, v73, v170
	s_waitcnt lgkmcnt(2)
	v_mfma_f32_32x32x16_bf16 v[176:191], v[224:227], v[108:111], v[176:191]
	v_cvt_pk_bf16_f32 v133, v74, v75
	v_add_f32_e32 v170, v74, v170
	v_mfma_f32_32x32x16_bf16 v[192:207], v[228:231], v[108:111], v[192:207]
	ds_read_b128 v[240:243], v157 offset:24576
	ds_read_b128 v[244:247], v157 offset:32768
	v_cvt_pk_bf16_f32 v134, v76, v77
	v_add_f32_e32 v170, v75, v170
	v_cvt_pk_bf16_f32 v135, v78, v79
	s_waitcnt lgkmcnt(2)
	v_mfma_f32_32x32x16_bf16 v[176:191], v[232:235], v[112:115], v[176:191]
	v_add_f32_e32 v170, v76, v170
	v_add_f32_e32 v170, v77, v170
	v_mfma_f32_32x32x16_bf16 v[192:207], v[236:239], v[112:115], v[192:207]
	ds_read_b128 v[224:227], v158 offset:24576
	ds_read_b128 v[228:231], v158 offset:32768
	v_add_f32_e32 v170, v78, v170
	v_add_f32_e32 v170, v79, v170
	ds_read_b64_tr_b16 v[64:65], v164 offset:0
	ds_read_b64_tr_b16 v[66:67], v164 offset:2048
	ds_read_b64_tr_b16 v[68:69], v164 offset:4096
	ds_read_b64_tr_b16 v[70:71], v164 offset:6144
	s_waitcnt lgkmcnt(6)
	v_mfma_f32_32x32x16_bf16 v[176:191], v[240:243], v[116:119], v[176:191]
	v_add_f32_e32 v171, v80, v81
	v_permlane32_swap_b32_e32 v128, v130
	v_mfma_f32_32x32x16_bf16 v[192:207], v[244:247], v[116:119], v[192:207]
	ds_read_b128 v[232:235], v159 offset:24576
	ds_read_b128 v[236:239], v159 offset:32768
	v_add_f32_e32 v171, v82, v171
	v_permlane32_swap_b32_e32 v129, v131
	v_add_f32_e32 v171, v83, v171
	s_waitcnt lgkmcnt(6)
	v_mfma_f32_32x32x16_bf16 v[176:191], v[224:227], v[120:123], v[176:191]
	v_permlane32_swap_b32_e32 v132, v134
	v_add_f32_e32 v171, v84, v171
	v_permlane32_swap_b32_e32 v133, v135
	v_mfma_f32_32x32x16_bf16 v[192:207], v[228:231], v[120:123], v[192:207]
	ds_read_b128 v[252:255], v248 offset:0
	ds_read_b128 v[240:243], v160 offset:40960
	ds_read_b128 v[244:247], v160 offset:45056
	v_add_f32_e32 v171, v85, v171
	v_add_f32_e32 v171, v86, v171
	s_waitcnt lgkmcnt(3)
	v_mfma_f32_32x32x16_bf16 v[176:191], v[232:235], v[124:127], v[176:191]
	v_add_f32_e32 v171, v87, v171
	v_add_f32_e32 v171, v88, v171
	ds_read_b64_tr_b16 v[72:73], v164 offset:8192
	ds_read_b64_tr_b16 v[74:75], v164 offset:10240
	ds_read_b64_tr_b16 v[76:77], v164 offset:12288
	ds_read_b64_tr_b16 v[78:79], v164 offset:14336
	v_mfma_f32_32x32x16_bf16 v[192:207], v[236:239], v[124:127], v[192:207]
	ds_read_b128 v[144:147], v248 offset:1024
	ds_read_b128 v[224:227], v161 offset:40960
	ds_read_b128 v[228:231], v161 offset:45056
	v_add_f32_e32 v171, v89, v171
	v_cvt_pk_bf16_f32 v136, v80, v81
	s_waitcnt lgkmcnt(7)
; #define SBAR() __builtin_amdgcn_sched_barrier(0)
; __device__ __forceinline__ void partialSM(f32x16& p0, f32x16& p1, float& m_reg, float& alpha, const float C, const float THRS) {
;   float pmax = p0[0];
; #pragma unroll
;   for (int r = 1; r < 16; ++r) pmax = fmaxf(pmax, p0[r]);
; #pragma unroll
;   for (int r = 0; r < 16; ++r) pmax = fmaxf(pmax, p1[r]);
;   { auto rr = __builtin_amdgcn_permlane32_swap(__float_as_uint(pmax), __float_as_uint(pmax), false, false);
;     pmax = fmaxf(__uint_as_float(rr[0]), __uint_as_float(rr[1])); }
;   float mn;
;   if (__builtin_expect(__all(pmax - m_reg <= THRS), 1)) { mn = m_reg; alpha = 1.f; }
;   else { mn = fmaxf(m_reg, pmax); alpha = __builtin_amdgcn_exp2f((m_reg - mn) * C); m_reg = mn; }
; template <int OFF> __device__ __forceinline__ s16x4 tr_read(int vb) {
;   s16x4 r; asm volatile("ds_read_b64_tr_b16 %0, %1 offset:%2" : "=&v"(r) : "v"(vb), "i"(OFF) : "memory"); return r;
; }
; template <int D0, int NCB> __device__ __forceinline__ void pv_one(f32x16& od, int vb, bf16x8 pa0, bf16x8 pa1, bf16x8 pa2, bf16x8 pa3) {
;   const s16x4 l0 = tr_read<v_rd_off<NCB>(D0, 0, 0)>(vb), h0 = tr_read<v_rd_off<NCB>(D0, 0, 1)>(vb), l1 = tr_read<v_rd_off<NCB>(D0, 1, 0)>(vb), h1 = tr_read<v_rd_off<NCB>(D0, 1, 1)>(vb);
;   const s16x4 l2 = tr_read<v_rd_off<NCB>(D0, 2, 0)>(vb), h2 = tr_read<v_rd_off<NCB>(D0, 2, 1)>(vb), l3 = tr_read<v_rd_off<NCB>(D0, 3, 0)>(vb), h3 = tr_read<v_rd_off<NCB>(D0, 3, 1)>(vb);
;   asm volatile("s_waitcnt lgkmcnt(0)" ::: "memory"); SBAR();
;     ...
;   od = __builtin_amdgcn_mfma_f32_32x32x16_bf16(pa0, PK(l0, h0), od, 0, 0, 0);
;   od = __builtin_amdgcn_mfma_f32_32x32x16_bf16(pa1, PK(l1, h1), od, 0, 0, 0);
;   od = __builtin_amdgcn_mfma_f32_32x32x16_bf16(pa2, PK(l2, h2), od, 0, 0, 0);
;   od = __builtin_amdgcn_mfma_f32_32x32x16_bf16(pa3, PK(l3, h3), od, 0, 0, 0);
;     ...
; }
; template <int NCB> __device__ __forceinline__ void pv_all(f32x16* o, int vb, bf16x8 pa0, bf16x8 pa1, bf16x8 pa2, bf16x8 pa3) {
;   pv_one<0, NCB>(o[0], vb, pa0, pa1, pa2, pa3); pv_one<1, NCB>(o[1], vb, pa0, pa1, pa2, pa3);
;   if constexpr (NCB == 4) { pv_one<2, NCB>(o[2], vb, pa0, pa1, pa2, pa3); pv_one<3, NCB>(o[3], vb, pa0, pa1, pa2, pa3); }
; }
	v_mfma_f32_32x32x16_bf16 v[176:191], v[240:243], v[252:255], v[176:191]
	v_add_f32_e32 v171, v90, v171
	v_cvt_pk_bf16_f32 v137, v82, v83
	v_add_f32_e32 v171, v91, v171
	v_mfma_f32_32x32x16_bf16 v[192:207], v[244:247], v[252:255], v[192:207]
	ds_read_b128 v[148:151], v248 offset:2048
	ds_read_b128 v[232:235], v162 offset:40960
	ds_read_b128 v[236:239], v162 offset:45056
	v_cvt_pk_bf16_f32 v138, v84, v85
	v_add_f32_e32 v171, v92, v171
	s_waitcnt lgkmcnt(3)
	v_mfma_f32_32x32x16_bf16 v[176:191], v[224:227], v[144:147], v[176:191]
	v_cvt_pk_bf16_f32 v139, v86, v87
	v_add_f32_e32 v171, v93, v171
	v_cvt_pk_bf16_f32 v140, v88, v89
	v_mfma_f32_32x32x16_bf16 v[192:207], v[228:231], v[144:147], v[192:207]
	ds_read_b128 v[252:255], v248 offset:3072
	ds_read_b128 v[240:243], v163 offset:40960
	ds_read_b128 v[244:247], v163 offset:45056
	v_add_f32_e32 v171, v94, v171
	v_cvt_pk_bf16_f32 v141, v90, v91
	s_waitcnt lgkmcnt(3)
	v_mfma_f32_32x32x16_bf16 v[176:191], v[232:235], v[148:151], v[176:191]
	v_add_f32_e32 v171, v95, v171
	v_cvt_pk_bf16_f32 v142, v92, v93
	v_add_f32_e32 v170, v171, v170
	v_mfma_f32_32x32x16_bf16 v[192:207], v[236:239], v[148:151], v[192:207]
	v_cvt_pk_bf16_f32 v143, v94, v95
	s_nop 0
	s_waitcnt lgkmcnt(0)
	v_mfma_f32_32x32x16_bf16 v[176:191], v[240:243], v[252:255], v[176:191]
	v_permlane32_swap_b32_e32 v136, v138
	v_permlane32_swap_b32_e32 v137, v139
	v_permlane32_swap_b32_e32 v140, v142
	v_mfma_f32_32x32x16_bf16 v[192:207], v[244:247], v[252:255], v[192:207]
	v_permlane32_swap_b32_e32 v141, v143
	ds_read_b64_tr_b16 v[80:81], v164 offset:512
	ds_read_b64_tr_b16 v[82:83], v164 offset:2560
	ds_read_b64_tr_b16 v[84:85], v164 offset:4608
	ds_read_b64_tr_b16 v[86:87], v164 offset:6656
	ds_read_b64_tr_b16 v[88:89], v164 offset:8704
	ds_read_b64_tr_b16 v[90:91], v164 offset:10752
	ds_read_b64_tr_b16 v[92:93], v164 offset:12800
	ds_read_b64_tr_b16 v[94:95], v164 offset:14848
	s_waitcnt lgkmcnt(15)
	v_mfma_f32_32x32x16_bf16 v[0:15], v[128:131], v[64:67], v[0:15]
	v_mfma_f32_32x32x16_bf16 v[0:15], v[132:135], v[68:71], v[0:15]
	ds_read_b64_tr_b16 v[64:65], v164 offset:1024
	ds_read_b64_tr_b16 v[66:67], v164 offset:3072
	ds_read_b64_tr_b16 v[68:69], v164 offset:5120
	ds_read_b64_tr_b16 v[70:71], v164 offset:7168
	v_mfma_f32_32x32x16_bf16 v[0:15], v[136:139], v[72:75], v[0:15]
	v_mfma_f32_32x32x16_bf16 v[0:15], v[140:143], v[76:79], v[0:15]
	ds_read_b64_tr_b16 v[72:73], v164 offset:9216
	ds_read_b64_tr_b16 v[74:75], v164 offset:11264
	ds_read_b64_tr_b16 v[76:77], v164 offset:13312
	ds_read_b64_tr_b16 v[78:79], v164 offset:15360
	s_waitcnt lgkmcnt(8)
	v_mfma_f32_32x32x16_bf16 v[48:63], v[128:131], v[80:83], v[48:63]
	v_max3_f32 v224, v176, v177, v178
	v_max3_f32 v225, v192, v193, v194
	v_max3_f32 v224, v224, v179, v180
	v_max3_f32 v225, v225, v195, v196
	v_max3_f32 v224, v224, v181, v182
	v_mfma_f32_32x32x16_bf16 v[48:63], v[132:135], v[84:87], v[48:63]
	v_max3_f32 v225, v225, v197, v198
	v_max3_f32 v224, v224, v183, v184
	v_max3_f32 v225, v225, v199, v200
	v_max3_f32 v224, v224, v185, v186
	v_max3_f32 v225, v225, v201, v202
	ds_read_b64_tr_b16 v[80:81], v164 offset:1536
	ds_read_b64_tr_b16 v[82:83], v164 offset:3584
	ds_read_b64_tr_b16 v[84:85], v164 offset:5632
	ds_read_b64_tr_b16 v[86:87], v164 offset:7680
	v_mfma_f32_32x32x16_bf16 v[48:63], v[136:139], v[88:91], v[48:63]
	v_max3_f32 v224, v224, v187, v188
	v_max3_f32 v225, v225, v203, v204
	v_max3_f32 v224, v224, v189, v190
	v_max3_f32 v225, v225, v205, v206
	v_max_f32_e32 v224, v191, v224
	v_mfma_f32_32x32x16_bf16 v[48:63], v[140:143], v[92:95], v[48:63]
	v_max_f32_e32 v225, v207, v225
	v_max_f32_e32 v226, v224, v225
	v_mov_b32_e32 v227, v226
	s_nop 1
	v_permlane32_swap_b32_e32 v226, v227
	v_max_f32_e32 v226, v226, v227
	ds_read_b64_tr_b16 v[88:89], v164 offset:9728
	ds_read_b64_tr_b16 v[90:91], v164 offset:11776
	ds_read_b64_tr_b16 v[92:93], v164 offset:13824
	ds_read_b64_tr_b16 v[94:95], v164 offset:15872
	s_waitcnt lgkmcnt(8)
	v_mfma_f32_32x32x16_bf16 v[32:47], v[128:131], v[64:67], v[32:47]
	v_cmp_lt_f32_e32 vcc, 0x4138aa3b, v226
	s_cbranch_vccnz .Lat_r1_lb
